# FF2 tail: fall-through skip stubs + epilogue loads issued before the realign barriers
# speedup vs baseline: 1.0057x; 1.0008x over previous
.LBB0_615:
	v_add_u32_e32 v151, s51, v149
	ds_read_b128 v[152:155], v151
	ds_read_b128 v[156:159], v151 offset:1024
	ds_read_b128 v[160:163], v151 offset:2048
	ds_read_b128 v[164:167], v151 offset:3072
	v_add_u32_e32 v151, s56, v149
	ds_read_b128 v[168:171], v151
	ds_read_b128 v[172:175], v151 offset:1024
	ds_read_b128 v[176:179], v151 offset:2048
	ds_read_b128 v[180:183], v151 offset:3072
	s_add_u32 s38, s12, s36
	s_addc_u32 s39, s13, s37
	s_cmp_eq_u32 s63, 60
	s_cselect_b32 s42, s59, s38
	s_cselect_b32 s43, s23, s39
	s_cselect_b32 s40, s60, s61
	s_cselect_b32 s41, s21, s62
	s_add_u32 s38, s42, 0x8000
	s_addc_u32 s39, s43, 0
	s_add_i32 m0, s44, 0xc000
	ds_read_b128 v[184:187], v150
	ds_read_b128 v[188:191], v150 offset:1024
	ds_read_b128 v[192:195], v150 offset:2048
	ds_read_b128 v[196:199], v150 offset:3072
	ds_read_b128 v[200:203], v150 offset:4096
	ds_read_b128 v[204:207], v150 offset:5120
	ds_read_b128 v[208:211], v150 offset:6144
	ds_read_b128 v[212:215], v150 offset:7168
	global_load_lds_dwordx4 v146, s[12:13]
	s_add_i32 m0, s44, 0xe000
	s_nop 0
	global_load_lds_dwordx4 v144, s[12:13]
	s_waitcnt vmcnt(8)
	s_waitcnt lgkmcnt(0)
	s_setprio 1
	s_barrier
	v_mfma_f32_16x16x32_bf16 v[124:127], v[152:155], v[184:187], v[124:127]
	v_mfma_f32_16x16x32_bf16 v[120:123], v[160:163], v[184:187], v[120:123]
	v_mfma_f32_16x16x32_bf16 v[108:111], v[152:155], v[192:195], v[108:111]
	v_mfma_f32_16x16x32_bf16 v[104:107], v[160:163], v[192:195], v[104:107]
	v_mfma_f32_16x16x32_bf16 v[92:95], v[152:155], v[200:203], v[92:95]
	v_mfma_f32_16x16x32_bf16 v[88:91], v[160:163], v[200:203], v[88:91]
	v_mfma_f32_16x16x32_bf16 v[76:79], v[152:155], v[208:211], v[76:79]
	v_mfma_f32_16x16x32_bf16 v[72:75], v[160:163], v[208:211], v[72:75]
	v_mfma_f32_16x16x32_bf16 v[124:127], v[156:159], v[188:191], v[124:127]
	v_mfma_f32_16x16x32_bf16 v[120:123], v[164:167], v[188:191], v[120:123]
	v_mfma_f32_16x16x32_bf16 v[108:111], v[156:159], v[196:199], v[108:111]
	v_mfma_f32_16x16x32_bf16 v[104:107], v[164:167], v[196:199], v[104:107]
	v_mfma_f32_16x16x32_bf16 v[92:95], v[156:159], v[204:207], v[92:95]
	v_mfma_f32_16x16x32_bf16 v[88:91], v[164:167], v[204:207], v[88:91]
	v_mfma_f32_16x16x32_bf16 v[76:79], v[156:159], v[212:215], v[76:79]
	v_mfma_f32_16x16x32_bf16 v[72:75], v[164:167], v[212:215], v[72:75]
	v_mfma_f32_16x16x32_bf16 v[116:119], v[168:171], v[184:187], v[116:119]
	v_mfma_f32_16x16x32_bf16 v[112:115], v[176:179], v[184:187], v[112:115]
	v_mfma_f32_16x16x32_bf16 v[100:103], v[168:171], v[192:195], v[100:103]
	v_mfma_f32_16x16x32_bf16 v[96:99], v[176:179], v[192:195], v[96:99]
	v_mfma_f32_16x16x32_bf16 v[84:87], v[168:171], v[200:203], v[84:87]
	v_mfma_f32_16x16x32_bf16 v[80:83], v[176:179], v[200:203], v[80:83]
	v_mfma_f32_16x16x32_bf16 v[68:71], v[168:171], v[208:211], v[68:71]
	v_mfma_f32_16x16x32_bf16 v[64:67], v[176:179], v[208:211], v[64:67]
	v_mfma_f32_16x16x32_bf16 v[116:119], v[172:175], v[188:191], v[116:119]
	v_mfma_f32_16x16x32_bf16 v[112:115], v[180:183], v[188:191], v[112:115]
	v_mfma_f32_16x16x32_bf16 v[100:103], v[172:175], v[196:199], v[100:103]
	v_mfma_f32_16x16x32_bf16 v[96:99], v[180:183], v[196:199], v[96:99]
	v_mfma_f32_16x16x32_bf16 v[84:87], v[172:175], v[204:207], v[84:87]
	v_mfma_f32_16x16x32_bf16 v[80:83], v[180:183], v[204:207], v[80:83]
	v_mfma_f32_16x16x32_bf16 v[68:71], v[172:175], v[212:215], v[68:71]
	v_mfma_f32_16x16x32_bf16 v[64:67], v[180:183], v[212:215], v[64:67]
	s_barrier
	s_setprio 0
	s_add_i32 s64, s51, s35
	s_mov_b32 m0, s64
	ds_read_b128 v[184:187], v150 offset:16384
	ds_read_b128 v[188:191], v150 offset:17408
	ds_read_b128 v[192:195], v150 offset:18432
	ds_read_b128 v[196:199], v150 offset:19456
	ds_read_b128 v[200:203], v150 offset:20480
	ds_read_b128 v[204:207], v150 offset:21504
	ds_read_b128 v[208:211], v150 offset:22528
	ds_read_b128 v[212:215], v150 offset:23552
	s_cmp_eq_u32 s63, 60
	s_cbranch_scc1 .Lff2_last0

.Lff2_join0:
	s_waitcnt vmcnt(8)
	s_waitcnt lgkmcnt(0)
	s_setprio 1
	s_barrier
	v_mfma_f32_16x16x32_bf16 v[60:63], v[152:155], v[184:187], v[60:63]
	v_mfma_f32_16x16x32_bf16 v[56:59], v[160:163], v[184:187], v[56:59]
	v_mfma_f32_16x16x32_bf16 v[44:47], v[152:155], v[192:195], v[44:47]
	v_mfma_f32_16x16x32_bf16 v[40:43], v[160:163], v[192:195], v[40:43]
	v_mfma_f32_16x16x32_bf16 v[28:31], v[152:155], v[200:203], v[28:31]
	v_mfma_f32_16x16x32_bf16 v[24:27], v[160:163], v[200:203], v[24:27]
	v_mfma_f32_16x16x32_bf16 v[12:15], v[152:155], v[208:211], v[12:15]
	v_mfma_f32_16x16x32_bf16 v[8:11], v[160:163], v[208:211], v[8:11]
	v_mfma_f32_16x16x32_bf16 v[60:63], v[156:159], v[188:191], v[60:63]
	v_mfma_f32_16x16x32_bf16 v[56:59], v[164:167], v[188:191], v[56:59]
	v_mfma_f32_16x16x32_bf16 v[44:47], v[156:159], v[196:199], v[44:47]
	v_mfma_f32_16x16x32_bf16 v[40:43], v[164:167], v[196:199], v[40:43]
	v_mfma_f32_16x16x32_bf16 v[28:31], v[156:159], v[204:207], v[28:31]
	v_mfma_f32_16x16x32_bf16 v[24:27], v[164:167], v[204:207], v[24:27]
	v_mfma_f32_16x16x32_bf16 v[12:15], v[156:159], v[212:215], v[12:15]
	v_mfma_f32_16x16x32_bf16 v[8:11], v[164:167], v[212:215], v[8:11]
	v_mfma_f32_16x16x32_bf16 v[52:55], v[168:171], v[184:187], v[52:55]
	v_mfma_f32_16x16x32_bf16 v[48:51], v[176:179], v[184:187], v[48:51]
	v_mfma_f32_16x16x32_bf16 v[36:39], v[168:171], v[192:195], v[36:39]
	v_mfma_f32_16x16x32_bf16 v[32:35], v[176:179], v[192:195], v[32:35]
	v_mfma_f32_16x16x32_bf16 v[20:23], v[168:171], v[200:203], v[20:23]
	v_mfma_f32_16x16x32_bf16 v[16:19], v[176:179], v[200:203], v[16:19]
	v_mfma_f32_16x16x32_bf16 v[4:7], v[168:171], v[208:211], v[4:7]
	v_mfma_f32_16x16x32_bf16 v[0:3], v[176:179], v[208:211], v[0:3]
	v_mfma_f32_16x16x32_bf16 v[52:55], v[172:175], v[188:191], v[52:55]
	v_mfma_f32_16x16x32_bf16 v[48:51], v[180:183], v[188:191], v[48:51]
	v_mfma_f32_16x16x32_bf16 v[36:39], v[172:175], v[196:199], v[36:39]
	v_mfma_f32_16x16x32_bf16 v[32:35], v[180:183], v[196:199], v[32:35]
	v_mfma_f32_16x16x32_bf16 v[20:23], v[172:175], v[204:207], v[20:23]
	v_mfma_f32_16x16x32_bf16 v[16:19], v[180:183], v[204:207], v[16:19]
	v_mfma_f32_16x16x32_bf16 v[4:7], v[172:175], v[212:215], v[4:7]
	v_mfma_f32_16x16x32_bf16 v[0:3], v[180:183], v[212:215], v[0:3]
	s_barrier
	s_setprio 0
	s_add_i32 s64, 0, 0x18000
	v_add_u32_e32 v151, s64, v149
	s_add_i32 s65, 0, 0x1c000
	ds_read_b128 v[152:155], v151
	ds_read_b128 v[156:159], v151 offset:1024
	ds_read_b128 v[160:163], v151 offset:2048
	ds_read_b128 v[164:167], v151 offset:3072
	v_add_u32_e32 v151, s65, v149
	ds_read_b128 v[168:171], v151
	ds_read_b128 v[172:175], v151 offset:1024
	ds_read_b128 v[176:179], v151 offset:2048
	ds_read_b128 v[180:183], v151 offset:3072
	s_add_u32 s42, s42, 0x2000
	s_addc_u32 s43, s43, 0
	s_mov_b32 m0, s46
	ds_read_b128 v[184:187], v150 offset:32768
	ds_read_b128 v[188:191], v150 offset:33792
	ds_read_b128 v[192:195], v150 offset:34816
	ds_read_b128 v[196:199], v150 offset:35840
	ds_read_b128 v[200:203], v150 offset:36864
	ds_read_b128 v[204:207], v150 offset:37888
	ds_read_b128 v[208:211], v150 offset:38912
	ds_read_b128 v[212:215], v150 offset:39936
	s_cmp_eq_u32 s63, 60
	s_cbranch_scc1 .Lff2_last1

.Lff2_join1:
	s_waitcnt vmcnt(8)
	s_waitcnt lgkmcnt(0)
	s_setprio 1
	s_barrier
	v_mfma_f32_16x16x32_bf16 v[124:127], v[152:155], v[184:187], v[124:127]
	v_mfma_f32_16x16x32_bf16 v[120:123], v[160:163], v[184:187], v[120:123]
	v_mfma_f32_16x16x32_bf16 v[108:111], v[152:155], v[192:195], v[108:111]
	v_mfma_f32_16x16x32_bf16 v[104:107], v[160:163], v[192:195], v[104:107]
	v_mfma_f32_16x16x32_bf16 v[92:95], v[152:155], v[200:203], v[92:95]
	v_mfma_f32_16x16x32_bf16 v[88:91], v[160:163], v[200:203], v[88:91]
	v_mfma_f32_16x16x32_bf16 v[76:79], v[152:155], v[208:211], v[76:79]
	v_mfma_f32_16x16x32_bf16 v[72:75], v[160:163], v[208:211], v[72:75]
	v_mfma_f32_16x16x32_bf16 v[124:127], v[156:159], v[188:191], v[124:127]
	v_mfma_f32_16x16x32_bf16 v[120:123], v[164:167], v[188:191], v[120:123]
	v_mfma_f32_16x16x32_bf16 v[108:111], v[156:159], v[196:199], v[108:111]
	v_mfma_f32_16x16x32_bf16 v[104:107], v[164:167], v[196:199], v[104:107]
	v_mfma_f32_16x16x32_bf16 v[92:95], v[156:159], v[204:207], v[92:95]
	v_mfma_f32_16x16x32_bf16 v[88:91], v[164:167], v[204:207], v[88:91]
	v_mfma_f32_16x16x32_bf16 v[76:79], v[156:159], v[212:215], v[76:79]
	v_mfma_f32_16x16x32_bf16 v[72:75], v[164:167], v[212:215], v[72:75]
	v_mfma_f32_16x16x32_bf16 v[116:119], v[168:171], v[184:187], v[116:119]
	v_mfma_f32_16x16x32_bf16 v[112:115], v[176:179], v[184:187], v[112:115]
	v_mfma_f32_16x16x32_bf16 v[100:103], v[168:171], v[192:195], v[100:103]
	v_mfma_f32_16x16x32_bf16 v[96:99], v[176:179], v[192:195], v[96:99]
	v_mfma_f32_16x16x32_bf16 v[84:87], v[168:171], v[200:203], v[84:87]
	v_mfma_f32_16x16x32_bf16 v[80:83], v[176:179], v[200:203], v[80:83]
	v_mfma_f32_16x16x32_bf16 v[68:71], v[168:171], v[208:211], v[68:71]
	v_mfma_f32_16x16x32_bf16 v[64:67], v[176:179], v[208:211], v[64:67]
	v_mfma_f32_16x16x32_bf16 v[116:119], v[172:175], v[188:191], v[116:119]
	v_mfma_f32_16x16x32_bf16 v[112:115], v[180:183], v[188:191], v[112:115]
	v_mfma_f32_16x16x32_bf16 v[100:103], v[172:175], v[196:199], v[100:103]
	v_mfma_f32_16x16x32_bf16 v[96:99], v[180:183], v[196:199], v[96:99]
	v_mfma_f32_16x16x32_bf16 v[84:87], v[172:175], v[204:207], v[84:87]
	v_mfma_f32_16x16x32_bf16 v[80:83], v[180:183], v[204:207], v[80:83]
	v_mfma_f32_16x16x32_bf16 v[68:71], v[172:175], v[212:215], v[68:71]
	v_mfma_f32_16x16x32_bf16 v[64:67], v[180:183], v[212:215], v[64:67]
	s_barrier
	s_setprio 0
	s_add_u32 s98, s40, s16
	s_addc_u32 s99, s41, s17
	s_add_i32 s42, s64, s35
	s_mov_b32 m0, s42
	ds_read_b128 v[184:187], v150 offset:49152
	ds_read_b128 v[188:191], v150 offset:50176
	ds_read_b128 v[192:195], v150 offset:51200
	ds_read_b128 v[196:199], v150 offset:52224
	ds_read_b128 v[200:203], v150 offset:53248
	ds_read_b128 v[204:207], v150 offset:54272
	ds_read_b128 v[208:211], v150 offset:55296
	ds_read_b128 v[212:215], v150 offset:56320
	s_cmp_eq_u32 s63, 60
	s_cbranch_scc1 .Lff2_last2

.Lff2_last0:
	s_waitcnt vmcnt(2)
	s_branch .Lff2_join0
.Lff2_last1:
	s_waitcnt vmcnt(0)
	s_branch .Lff2_join1

.LBB0_618:
	s_waitcnt vmcnt(0)
	v_ashrrev_i32_e32 v229, 4, v228
	s_lshl_b32 s0, s9, 5
	s_lshl_b32 s1, s8, 8
	s_or_b32 s0, s1, s0
	v_lshlrev_b32_e32 v144, 3, v229
	v_add_u32_e32 v128, s0, v144
	s_lshr_b32 s0, s6, 4
	s_mulk_i32 s0, 0x1800
	s_ashr_i32 s1, s0, 31
	s_lshl_b64 s[0:1], s[0:1], 2
	s_add_u32 s0, s54, s0
	v_ashrrev_i32_e32 v129, 31, v128
	s_addc_u32 s1, s55, s1
	v_lshlrev_b64 v[212:213], 2, v[128:129]
	v_lshl_add_u64 v[146:147], s[0:1], 0, v[212:213]
	s_mov_b64 s[0:1], 0x285000
	v_lshl_add_u64 v[132:133], v[146:147], 0, s[0:1]
	s_mov_b32 s0, 0x285000
	v_add_co_u32_e32 v128, vcc, s0, v146
	s_mov_b32 s0, 0x284000
	s_nop 0
	v_addc_co_u32_e32 v129, vcc, 0, v147, vcc
	v_add_co_u32_e32 v150, vcc, s0, v146
	v_readlane_b32 s12, v251, 2
	s_nop 0
	v_addc_co_u32_e32 v151, vcc, 0, v147, vcc
	v_readlane_b32 s20, v251, 10
	v_readlane_b32 s21, v251, 11
	global_load_dwordx4 v[136:139], v[128:129], off
	s_nop 0
	global_load_dwordx4 v[128:131], v[132:133], off offset:528
	global_load_dwordx4 v[140:143], v[132:133], off offset:16
	s_nop 0
	global_load_dwordx4 v[132:135], v[132:133], off offset:512
	v_lshl_add_u64 v[216:217], s[20:21], 0, v[212:213]
	global_load_dwordx4 v[218:221], v[150:151], off
	global_load_dwordx4 v[208:211], v[216:217], off offset:16
	global_load_dwordx4 v[222:225], v[216:217], off
	v_add_u32_e32 v214, s7, v148
	s_ashr_i32 s7, s6, 31
	s_lshl_b64 s[0:1], s[6:7], 19
	s_add_u32 s0, s54, s0
	s_addc_u32 s1, s55, s1
	s_lshl_b32 s2, s8, 3
	s_or_b32 s2, s2, s9
	v_ashrrev_i32_e32 v145, 31, v144
	s_ashr_i32 s3, s2, 31
	v_ashrrev_i32_e32 v215, 31, v214
	v_lshl_add_u64 v[144:145], v[144:145], 1, s[0:1]
	s_lshl_b64 s[0:1], s[2:3], 14
	v_lshlrev_b64 v[148:149], 6, v[214:215]
	s_or_b32 s2, s2, 4
	v_lshl_add_u64 v[144:145], v[144:145], 0, v[148:149]
	s_mov_b64 s[4:5], 0x4c00000
	s_ashr_i32 s3, s2, 31
	v_lshl_add_u64 v[148:149], v[144:145], 0, s[4:5]
	s_lshl_b64 s[2:3], s[2:3], 14
	v_lshl_add_u64 v[150:151], v[148:149], 0, s[0:1]
	v_lshl_add_u64 v[148:149], v[148:149], 0, s[2:3]
	s_mov_b64 s[4:5], 0x4c00400
	global_load_dwordx4 v[204:207], v[150:151], off nt
	global_load_dwordx4 v[200:203], v[148:149], off nt
	v_lshl_add_u64 v[148:149], v[144:145], 0, s[4:5]
	v_lshl_add_u64 v[150:151], v[148:149], 0, s[0:1]
	v_lshl_add_u64 v[148:149], v[148:149], 0, s[2:3]
	s_mov_b64 s[4:5], 0x4c00800
	global_load_dwordx4 v[196:199], v[150:151], off nt
	global_load_dwordx4 v[192:195], v[148:149], off nt
	v_lshl_add_u64 v[148:149], v[144:145], 0, s[4:5]
	v_lshl_add_u64 v[150:151], v[148:149], 0, s[0:1]
	v_lshl_add_u64 v[148:149], v[148:149], 0, s[2:3]
	s_mov_b64 s[4:5], 0x4c00c00
	global_load_dwordx4 v[188:191], v[150:151], off nt
	global_load_dwordx4 v[184:187], v[148:149], off nt
	v_lshl_add_u64 v[148:149], v[144:145], 0, s[4:5]
	v_lshl_add_u64 v[150:151], v[148:149], 0, s[0:1]
	v_lshl_add_u64 v[148:149], v[148:149], 0, s[2:3]
	s_mov_b64 s[4:5], 0x4c02000
	global_load_dwordx4 v[180:183], v[150:151], off nt
	global_load_dwordx4 v[176:179], v[148:149], off nt
	v_lshl_add_u64 v[148:149], v[144:145], 0, s[4:5]
	v_lshl_add_u64 v[150:151], v[148:149], 0, s[0:1]
	v_lshl_add_u64 v[148:149], v[148:149], 0, s[2:3]
	s_mov_b64 s[4:5], 0x4c02400
	global_load_dwordx4 v[172:175], v[150:151], off nt
	global_load_dwordx4 v[168:171], v[148:149], off nt
	v_lshl_add_u64 v[148:149], v[144:145], 0, s[4:5]
	v_lshl_add_u64 v[150:151], v[148:149], 0, s[0:1]
	v_lshl_add_u64 v[148:149], v[148:149], 0, s[2:3]
	s_mov_b64 s[4:5], 0x4c02800
	global_load_dwordx4 v[164:167], v[150:151], off nt
	global_load_dwordx4 v[160:163], v[148:149], off nt
	v_lshl_add_u64 v[148:149], v[144:145], 0, s[4:5]
	s_mov_b64 s[4:5], 0x284000
	v_lshl_add_u64 v[226:227], v[146:147], 0, s[4:5]
	v_lshl_add_u64 v[150:151], v[148:149], 0, s[0:1]
	v_lshl_add_u64 v[148:149], v[148:149], 0, s[2:3]
	global_load_dwordx4 v[230:233], v[226:227], off offset:16
	global_load_dwordx4 v[156:159], v[150:151], off nt
	global_load_dwordx4 v[152:155], v[148:149], off nt
	s_mov_b64 s[4:5], 0x4c02c00
	v_lshl_add_u64 v[144:145], v[144:145], 0, s[4:5]
	v_lshl_add_u64 v[146:147], v[144:145], 0, s[0:1]
	v_lshl_add_u64 v[144:145], v[144:145], 0, s[2:3]
	global_load_dwordx4 v[148:151], v[146:147], off nt
	s_nop 0
	global_load_dwordx4 v[144:147], v[144:145], off nt
	s_nop 0
	global_load_dwordx4 v[234:237], v[226:227], off offset:528
	v_readlane_b32 s13, v251, 3
	v_readlane_b32 s14, v251, 4
	v_readlane_b32 s15, v251, 5
	v_readlane_b32 s16, v251, 6
	v_readlane_b32 s17, v251, 7
	v_readlane_b32 s18, v251, 8
	v_readlane_b32 s19, v251, 9
	v_readlane_b32 s22, v251, 12
	v_readlane_b32 s23, v251, 13
	v_readlane_b32 s24, v251, 14
	v_readlane_b32 s25, v251, 15
	v_readlane_b32 s26, v251, 16
	v_readlane_b32 s27, v251, 17
	s_cmpk_gt_u32 s96, 0xff
	s_cbranch_scc1 .LBB0_620
	s_barrier
.LBB0_620:
	s_barrier
	s_waitcnt vmcnt(0)
	v_pk_add_f32 v[220:221], v[220:221], 1.0 op_sel_hi:[1,0]
	s_nop 0
	v_pk_mul_f32 v[242:243], v[224:225], v[220:221]
	v_pk_add_f32 v[218:219], v[218:219], 1.0 op_sel_hi:[1,0]
	v_div_scale_f32 v215, s[0:1], v242, v242, 1.0
	v_rcp_f32_e32 v220, v215
	v_pk_mul_f32 v[218:219], v[222:223], v[218:219]
	s_mov_b32 s0, 0xda24260
	v_div_scale_f32 v245, s[2:3], v219, v219, 1.0
	v_fma_f32 v221, -v215, v220, 1.0
	v_fmac_f32_e32 v220, v221, v220
	v_div_scale_f32 v221, vcc, 1.0, v242, 1.0
	v_mul_f32_e32 v222, v221, v220
	v_fma_f32 v223, -v215, v222, v221
	v_fmac_f32_e32 v222, v223, v220
	v_fma_f32 v215, -v215, v222, v221
	v_div_scale_f32 v221, s[2:3], v243, v243, 1.0
	v_rcp_f32_e32 v223, v221
	v_div_fmas_f32 v215, v215, v220, v222
	v_rcp_f32_e32 v246, v245
	v_div_fixup_f32 v215, v215, v242, 1.0
	v_fma_f32 v220, -v221, v223, 1.0
	v_fmac_f32_e32 v223, v220, v223
	v_div_scale_f32 v220, vcc, 1.0, v243, 1.0
	v_mul_f32_e32 v222, v220, v223
	v_fma_f32 v224, -v221, v222, v220
	v_fmac_f32_e32 v222, v224, v223
	v_fma_f32 v220, -v221, v222, v220
	v_div_scale_f32 v221, s[2:3], v218, v218, 1.0
	v_rcp_f32_e32 v224, v221
	v_div_fmas_f32 v220, v220, v223, v222
	v_div_fixup_f32 v244, v220, v243, 1.0
	v_fma_f32 v220, -v221, v224, 1.0
	v_fmac_f32_e32 v224, v220, v224
	v_div_scale_f32 v220, vcc, 1.0, v218, 1.0
	v_mul_f32_e32 v222, v220, v224
	v_fma_f32 v223, -v221, v222, v220
	v_fmac_f32_e32 v222, v223, v224
	v_fma_f32 v220, -v221, v222, v220
	v_div_fmas_f32 v220, v220, v224, v222
	v_div_fixup_f32 v247, v220, v218, 1.0
	v_fma_f32 v220, -v245, v246, 1.0
	v_fmac_f32_e32 v246, v220, v246
	v_div_scale_f32 v248, vcc, 1.0, v219, 1.0
	v_mul_f32_e32 v249, v248, v246
	v_fma_f32 v220, -v245, v249, v248
	v_fmac_f32_e32 v249, v220, v246
	global_load_dwordx4 v[220:223], v[226:227], off offset:512
	s_nop 0
	global_load_dwordx4 v[224:227], v[216:217], off offset:528
	global_load_dwordx4 v[238:241], v[216:217], off offset:512
	v_fma_f32 v216, -v245, v249, v248
	v_div_fmas_f32 v216, v216, v246, v249
	v_cmp_gt_f32_e64 vcc, |v243|, s0
	v_pk_add_f32 v[232:233], v[232:233], 1.0 op_sel_hi:[1,0]
	v_div_fixup_f32 v245, v216, v219, 1.0
	v_cndmask_b32_e32 v217, 0, v244, vcc
	v_cmp_gt_f32_e64 vcc, |v242|, s0
	v_pk_mul_f32 v[210:211], v[210:211], v[232:233]
	v_pk_add_f32 v[230:231], v[230:231], 1.0 op_sel_hi:[1,0]
	v_cndmask_b32_e32 v216, 0, v215, vcc
	v_div_scale_f32 v215, s[2:3], v210, v210, 1.0
	v_rcp_f32_e32 v232, v215
	v_cmp_gt_f32_e64 vcc, |v219|, s0
	v_pk_mul_f32 v[230:231], v[208:209], v[230:231]
	v_fma_f32 v208, -v215, v232, 1.0
	v_cndmask_b32_e32 v219, 0, v245, vcc
	v_cmp_gt_f32_e64 vcc, |v218|, s0
	v_fmac_f32_e32 v232, v208, v232
	s_waitcnt vmcnt(2)
	v_pk_add_f32 v[222:223], v[222:223], 1.0 op_sel_hi:[1,0]
	v_cndmask_b32_e32 v218, 0, v247, vcc
	v_div_scale_f32 v208, vcc, 1.0, v210, 1.0
	v_mul_f32_e32 v209, v208, v232
	v_fma_f32 v233, -v215, v209, v208
	v_fmac_f32_e32 v209, v233, v232
	v_fma_f32 v208, -v215, v209, v208
	v_div_scale_f32 v215, s[2:3], v211, v211, 1.0
	v_rcp_f32_e32 v233, v215
	v_div_fmas_f32 v208, v208, v232, v209
	v_div_fixup_f32 v208, v208, v210, 1.0
	s_waitcnt vmcnt(0)
	v_pk_mul_f32 v[222:223], v[240:241], v[222:223]
	v_fma_f32 v209, -v215, v233, 1.0
	v_fmac_f32_e32 v233, v209, v233
	v_div_scale_f32 v209, vcc, 1.0, v211, 1.0
	v_mul_f32_e32 v232, v209, v233
	v_fma_f32 v242, -v215, v232, v209
	v_fmac_f32_e32 v232, v242, v233
	v_fma_f32 v209, -v215, v232, v209
	v_div_scale_f32 v215, s[2:3], v230, v230, 1.0
	v_rcp_f32_e32 v242, v215
	v_div_fmas_f32 v209, v209, v233, v232
	v_div_fixup_f32 v209, v209, v211, 1.0
	v_pk_add_f32 v[220:221], v[220:221], 1.0 op_sel_hi:[1,0]
	v_fma_f32 v232, -v215, v242, 1.0
	v_fmac_f32_e32 v242, v232, v242
	v_div_scale_f32 v232, vcc, 1.0, v230, 1.0
	v_mul_f32_e32 v233, v232, v242
	v_fma_f32 v243, -v215, v233, v232
	v_fmac_f32_e32 v233, v243, v242
	v_fma_f32 v215, -v215, v233, v232
	v_div_scale_f32 v232, s[2:3], v231, v231, 1.0
	v_rcp_f32_e32 v243, v232
	v_div_fmas_f32 v215, v215, v242, v233
	v_div_fixup_f32 v215, v215, v230, 1.0
	v_fma_f32 v233, -v232, v243, 1.0
	v_fmac_f32_e32 v243, v233, v243
	v_div_scale_f32 v233, vcc, 1.0, v231, 1.0
	v_mul_f32_e32 v242, v233, v243
	v_fma_f32 v244, -v232, v242, v233
	v_fmac_f32_e32 v242, v244, v243
	v_fma_f32 v232, -v232, v242, v233
	v_div_fmas_f32 v232, v232, v243, v242
	v_cmp_gt_f32_e64 vcc, |v211|, s0
	v_div_fixup_f32 v232, v232, v231, 1.0
	s_nop 0
	v_cndmask_b32_e32 v209, 0, v209, vcc
	v_cmp_gt_f32_e64 vcc, |v210|, s0
	s_nop 1
	v_cndmask_b32_e32 v208, 0, v208, vcc
	v_cmp_gt_f32_e64 vcc, |v231|, s0
	s_nop 1
	v_cndmask_b32_e32 v211, 0, v232, vcc
	v_div_scale_f32 v232, s[2:3], v222, v222, 1.0
	v_rcp_f32_e32 v233, v232
	v_cmp_gt_f32_e64 vcc, |v230|, s0
	v_pk_mul_f32 v[230:231], v[238:239], v[220:221]
	s_nop 0
	v_cndmask_b32_e32 v210, 0, v215, vcc
	v_fma_f32 v215, -v232, v233, 1.0
	v_fmac_f32_e32 v233, v215, v233
	v_div_scale_f32 v215, vcc, 1.0, v222, 1.0
	v_mul_f32_e32 v220, v215, v233
	v_fma_f32 v221, -v232, v220, v215
	v_fmac_f32_e32 v220, v221, v233
	v_div_scale_f32 v221, s[2:3], v223, v223, 1.0
	v_fma_f32 v215, -v232, v220, v215
	v_rcp_f32_e32 v232, v221
	v_div_fmas_f32 v215, v215, v233, v220
	v_div_fixup_f32 v215, v215, v222, 1.0
	v_fma_f32 v220, -v221, v232, 1.0
	v_fmac_f32_e32 v232, v220, v232
	v_div_scale_f32 v220, vcc, 1.0, v223, 1.0
	v_mul_f32_e32 v233, v220, v232
	v_fma_f32 v238, -v221, v233, v220
	v_fmac_f32_e32 v233, v238, v232
	v_fma_f32 v220, -v221, v233, v220
	v_div_scale_f32 v221, s[2:3], v230, v230, 1.0
	v_rcp_f32_e32 v238, v221
	v_div_fmas_f32 v220, v220, v232, v233
	v_div_fixup_f32 v220, v220, v223, 1.0
	v_fma_f32 v232, -v221, v238, 1.0
	v_fmac_f32_e32 v238, v232, v238
	v_div_scale_f32 v232, vcc, 1.0, v230, 1.0
	v_mul_f32_e32 v233, v232, v238
	v_fma_f32 v239, -v221, v233, v232
	v_fmac_f32_e32 v233, v239, v238
	v_fma_f32 v221, -v221, v233, v232
	v_div_scale_f32 v232, s[2:3], v231, v231, 1.0
	v_rcp_f32_e32 v239, v232
	v_div_fmas_f32 v221, v221, v238, v233
	v_div_fixup_f32 v238, v221, v230, 1.0
	v_fma_f32 v221, -v232, v239, 1.0
	v_fmac_f32_e32 v239, v221, v239
	v_div_scale_f32 v221, vcc, 1.0, v231, 1.0
	v_mul_f32_e32 v233, v221, v239
	v_fma_f32 v240, -v232, v233, v221
	v_fmac_f32_e32 v233, v240, v239
	v_fma_f32 v221, -v232, v233, v221
	v_div_fmas_f32 v221, v221, v239, v233
	v_cmp_gt_f32_e64 vcc, |v223|, s0
	v_div_fixup_f32 v232, v221, v231, 1.0
	s_nop 0
	v_cndmask_b32_e32 v221, 0, v220, vcc
	v_cmp_gt_f32_e64 vcc, |v222|, s0
	s_nop 1
	v_cndmask_b32_e32 v220, 0, v215, vcc
	v_cmp_gt_f32_e64 vcc, |v231|, s0
	s_nop 1
	v_cndmask_b32_e32 v223, 0, v232, vcc
	v_pk_add_f32 v[232:233], v[236:237], 1.0 op_sel_hi:[1,0]
	v_cmp_gt_f32_e64 vcc, |v230|, s0
	v_pk_mul_f32 v[226:227], v[226:227], v[232:233]
	v_pk_add_f32 v[230:231], v[234:235], 1.0 op_sel_hi:[1,0]
	v_div_scale_f32 v215, s[2:3], v226, v226, 1.0
	v_rcp_f32_e32 v232, v215
	v_pk_mul_f32 v[230:231], v[224:225], v[230:231]
	v_cndmask_b32_e32 v222, 0, v238, vcc
	v_fma_f32 v224, -v215, v232, 1.0
	v_fmac_f32_e32 v232, v224, v232
	v_div_scale_f32 v224, vcc, 1.0, v226, 1.0
	v_mul_f32_e32 v225, v224, v232
	v_fma_f32 v233, -v215, v225, v224
	v_fmac_f32_e32 v225, v233, v232
	v_fma_f32 v215, -v215, v225, v224
	v_div_scale_f32 v224, s[2:3], v227, v227, 1.0
	v_rcp_f32_e32 v233, v224
	v_div_fmas_f32 v215, v215, v232, v225
	v_div_fixup_f32 v215, v215, v226, 1.0
	v_fma_f32 v225, -v224, v233, 1.0
	v_fmac_f32_e32 v233, v225, v233
	v_div_scale_f32 v225, vcc, 1.0, v227, 1.0
	v_mul_f32_e32 v232, v225, v233
	v_fma_f32 v234, -v224, v232, v225
	v_fmac_f32_e32 v232, v234, v233
	v_fma_f32 v224, -v224, v232, v225
	v_div_scale_f32 v225, s[2:3], v230, v230, 1.0
	v_rcp_f32_e32 v234, v225
	v_div_fmas_f32 v224, v224, v233, v232
	v_div_fixup_f32 v224, v224, v227, 1.0
	v_fma_f32 v232, -v225, v234, 1.0
	v_fmac_f32_e32 v234, v232, v234
	v_div_scale_f32 v232, vcc, 1.0, v230, 1.0
	v_mul_f32_e32 v233, v232, v234
	v_fma_f32 v235, -v225, v233, v232
	v_fmac_f32_e32 v233, v235, v234
	v_fma_f32 v225, -v225, v233, v232
	v_div_scale_f32 v232, s[2:3], v231, v231, 1.0
	v_rcp_f32_e32 v235, v232
	v_div_fmas_f32 v225, v225, v234, v233
	v_div_fixup_f32 v233, v225, v230, 1.0
	v_fma_f32 v225, -v232, v235, 1.0
	v_fmac_f32_e32 v235, v225, v235
	v_div_scale_f32 v225, vcc, 1.0, v231, 1.0
	v_mul_f32_e32 v234, v225, v235
	v_fma_f32 v236, -v232, v234, v225
	v_fmac_f32_e32 v234, v236, v235
	v_fma_f32 v225, -v232, v234, v225
	v_div_fmas_f32 v225, v225, v235, v234
	v_cmp_gt_f32_e64 vcc, |v227|, s0
	v_div_fixup_f32 v232, v225, v231, 1.0
	s_nop 0
	v_cndmask_b32_e32 v225, 0, v224, vcc
	v_cmp_gt_f32_e64 vcc, |v226|, s0
	s_nop 1
	v_cndmask_b32_e32 v224, 0, v215, vcc
	v_cmp_gt_f32_e64 vcc, |v231|, s0
	s_nop 1
	v_cndmask_b32_e32 v227, 0, v232, vcc
	v_cmp_gt_f32_e64 vcc, |v230|, s0
	s_nop 1
	v_cndmask_b32_e32 v226, 0, v233, vcc
	v_mbcnt_lo_u32_b32 v215, -1, 0
	v_mbcnt_hi_u32_b32 v234, -1, v215
	v_and_b32_e32 v230, 64, v234
	v_add_u32_e32 v235, 64, v230
	v_lshlrev_b32_e32 v230, 16, v204
	v_and_b32_e32 v231, 0xffff0000, v204
	v_lshlrev_b32_e32 v204, 16, v205
	v_and_b32_e32 v205, 0xffff0000, v205
	v_pk_mul_f32 v[204:205], v[216:217], v[204:205]
	v_pk_mul_f32 v[230:231], v[218:219], v[230:231]
	v_lshlrev_b32_e32 v232, 16, v206
	v_and_b32_e32 v233, 0xffff0000, v206
	v_pk_fma_f32 v[126:127], v[126:127], v[138:139], v[204:205]
	v_pk_fma_f32 v[124:125], v[124:125], v[136:137], v[230:231]
	v_pk_mul_f32 v[232:233], v[210:211], v[232:233]
	v_mul_f32_e32 v204, v125, v125
	v_mul_f32_e32 v205, v127, v127
	v_lshlrev_b32_e32 v206, 16, v207
	v_and_b32_e32 v207, 0xffff0000, v207
	v_pk_fma_f32 v[120:121], v[120:121], v[140:141], v[232:233]
	v_fmac_f32_e32 v204, v124, v124
	v_fmac_f32_e32 v205, v126, v126
	v_pk_mul_f32 v[206:207], v[208:209], v[206:207]
	v_add_f32_e32 v204, v204, v205
	v_mul_f32_e32 v205, v121, v121
	v_pk_fma_f32 v[122:123], v[122:123], v[142:143], v[206:207]
	v_fmac_f32_e32 v205, v120, v120
	v_add_f32_e32 v204, v204, v205
	v_mul_f32_e32 v205, v123, v123
	v_fmac_f32_e32 v205, v122, v122
	v_add_f32_e32 v230, v205, v204
	v_lshlrev_b32_e32 v204, 16, v200
	v_and_b32_e32 v205, 0xffff0000, v200
	v_lshlrev_b32_e32 v200, 16, v201
	v_and_b32_e32 v201, 0xffff0000, v201
	v_pk_mul_f32 v[200:201], v[220:221], v[200:201]
	v_pk_mul_f32 v[204:205], v[222:223], v[204:205]
	v_lshlrev_b32_e32 v206, 16, v202
	v_and_b32_e32 v207, 0xffff0000, v202
	v_pk_fma_f32 v[118:119], v[118:119], v[134:135], v[200:201]
	v_pk_fma_f32 v[116:117], v[116:117], v[132:133], v[204:205]
	v_pk_mul_f32 v[206:207], v[226:227], v[206:207]
	v_mul_f32_e32 v200, v117, v117
	v_mul_f32_e32 v201, v119, v119
	v_lshlrev_b32_e32 v202, 16, v203
	v_and_b32_e32 v203, 0xffff0000, v203
	v_pk_fma_f32 v[112:113], v[112:113], v[128:129], v[206:207]
	v_fmac_f32_e32 v200, v116, v116
	v_fmac_f32_e32 v201, v118, v118
	v_pk_mul_f32 v[202:203], v[224:225], v[202:203]
	v_add_f32_e32 v200, v200, v201
	v_mul_f32_e32 v201, v113, v113
	v_pk_fma_f32 v[114:115], v[114:115], v[130:131], v[202:203]
	v_fmac_f32_e32 v201, v112, v112
	v_xor_b32_e32 v215, 16, v234
	v_add_f32_e32 v200, v200, v201
	v_mul_f32_e32 v201, v115, v115
	v_cmp_lt_i32_e32 vcc, v215, v235
	v_fmac_f32_e32 v201, v114, v114
	v_add_f32_e32 v200, v201, v200
	v_cndmask_b32_e32 v215, v234, v215, vcc
	v_lshlrev_b32_e32 v215, 2, v215
	v_add_f32_e32 v200, v230, v200
	ds_bpermute_b32 v202, v215, v200
	v_xor_b32_e32 v201, 32, v234
	v_cmp_lt_i32_e32 vcc, v201, v235
	s_lshl_b32 s0, s9, 2
	s_add_i32 s0, s0, 0
	v_cndmask_b32_e32 v201, v234, v201, vcc
	v_lshlrev_b32_e32 v201, 2, v201
	s_waitcnt lgkmcnt(0)
	v_add_f32_e32 v202, v200, v202
	ds_bpermute_b32 v203, v201, v202
	v_cmp_eq_u32_e32 vcc, 0, v229
	v_lshl_add_u32 v200, v214, 4, s0
	s_and_saveexec_b64 s[0:1], vcc
	s_cbranch_execz .LBB0_622
	s_waitcnt lgkmcnt(0)
	v_add_f32_e32 v202, v202, v203
	ds_write_b32 v200, v202
